# fused-LN row statistics hand-generated: 4 rows in flight, packed f32 adds/fmas, 319 vs 752 instr
# speedup vs baseline: 1.0260x; 1.0091x over previous
;     __device__ __forceinline__ void fused(f32x4 (&acc)[2][2][4][2], const GUnit& u, int wr, int wc, int fr, int fq, LAS unsigned char* lds, int wid, int lane) const {
;         const int rl0 = wr * 64 + fr, cl0 = wc * 32 + 8 * fq, grow0 = u.pm * 256 + rl0, gcol0 = u.pn * 256 + cl0;
;         f16* H16 = (f16*)(ws + WS_H16);
;         { u32x4 hw[2][4][2];
; #pragma unroll
;         for (int ai = 0; ai < 2; ++ai)
; #pragma unroll
;             for (int m = 0; m < 4; ++m)
; #pragma unroll
;                 for (int bj = 0; bj < 2; ++bj) hw[ai][m][bj] = *(const u32x4*)(H16 + (size_t)(grow0 + ai * 128 + m * 16) * 1024 + gcol0 + bj * 128);
;         asm volatile("" ::: "memory");
; #pragma unroll
;         for (int ai = 0; ai < 2; ++ai)
; #pragma unroll
;             for (int m = 0; m < 4; ++m) {
; #pragma unroll
;                 for (int bj = 0; bj < 2; ++bj) { f32x4 h0, h1; unpk8(hw[ai][m][bj], h0, h1);
;                     acc[ai][bj][m][0] += ALPHA * h0; acc[ai][bj][m][1] += ALPHA * h1;
;                 }
;                 asm volatile("" : "+v"(acc[ai][0][m][0]), "+v"(acc[ai][0][m][1]), "+v"(acc[ai][1][m][0]), "+v"(acc[ai][1][m][1])); } }
.LBB0_432:
	s_andn2_b64 vcc, exec, s[2:3]
	s_cbranch_vccnz .LBB0_567
	v_mbcnt_lo_u32_b32 v32, -1, 0
	v_mbcnt_hi_u32_b32 v32, -1, v32
	s_lshl_b32 s2, s34, 8
	v_ashrrev_i32_e32 v34, 1, v32
	v_readlane_b32 s3, v251, 28
	v_and_or_b32 v233, v32, 15, s48
	v_and_b32_e32 v34, -8, v34
	s_lshl_b32 s14, s37, 8
	s_or_b32 s2, s2, s3
	v_add_u32_e32 v214, s14, v233
	v_add_u32_e32 v198, s2, v34
	v_readlane_b32 s2, v253, 4
	v_ashrrev_i32_e32 v199, 31, v198
	v_readlane_b32 s3, v253, 5
	v_ashrrev_i32_e32 v215, 31, v214
	v_lshlrev_b64 v[216:217], 11, v[214:215]
	v_lshl_add_u64 v[136:137], v[198:199], 1, s[2:3]
	v_lshl_add_u64 v[34:35], v[136:137], 0, v[216:217]
	global_load_dwordx4 v[192:195], v[34:35], off
	global_load_dwordx4 v[188:191], v[34:35], off offset:256
	v_or_b32_e32 v34, 16, v214
	v_ashrrev_i32_e32 v35, 31, v34
	v_lshlrev_b64 v[34:35], 11, v[34:35]
	v_lshl_add_u64 v[34:35], v[136:137], 0, v[34:35]
	global_load_dwordx4 v[184:187], v[34:35], off
	global_load_dwordx4 v[180:183], v[34:35], off offset:256
	v_or_b32_e32 v34, 32, v214
	v_ashrrev_i32_e32 v35, 31, v34
	v_lshlrev_b64 v[34:35], 11, v[34:35]
	v_lshl_add_u64 v[34:35], v[136:137], 0, v[34:35]
	global_load_dwordx4 v[176:179], v[34:35], off
	global_load_dwordx4 v[172:175], v[34:35], off offset:256
	v_or_b32_e32 v34, 48, v214
	v_ashrrev_i32_e32 v35, 31, v34
	v_lshlrev_b64 v[34:35], 11, v[34:35]
	v_lshl_add_u64 v[34:35], v[136:137], 0, v[34:35]
	global_load_dwordx4 v[168:171], v[34:35], off
	global_load_dwordx4 v[164:167], v[34:35], off offset:256
	v_add_u32_e32 v212, 0x80, v214
	v_ashrrev_i32_e32 v213, 31, v212
	v_lshlrev_b64 v[210:211], 11, v[212:213]
	v_lshl_add_u64 v[34:35], v[136:137], 0, v[210:211]
	global_load_dwordx4 v[160:163], v[34:35], off
	global_load_dwordx4 v[156:159], v[34:35], off offset:256
	v_add_u32_e32 v208, 0x90, v214
	v_ashrrev_i32_e32 v209, 31, v208
	v_lshlrev_b64 v[34:35], 11, v[208:209]
	v_lshl_add_u64 v[132:133], v[136:137], 0, v[34:35]
	global_load_dwordx4 v[152:155], v[132:133], off
	global_load_dwordx4 v[144:147], v[132:133], off offset:256
	v_add_u32_e32 v206, 0xa0, v214
	v_ashrrev_i32_e32 v207, 31, v206
	v_lshlrev_b64 v[204:205], 11, v[206:207]
	v_lshl_add_u64 v[132:133], v[136:137], 0, v[204:205]
	global_load_dwordx4 v[140:143], v[132:133], off
	s_nop 0
	global_load_dwordx4 v[132:135], v[132:133], off offset:256
	v_add_u32_e32 v200, 0xb0, v214
	v_ashrrev_i32_e32 v201, 31, v200
	v_lshlrev_b64 v[202:203], 11, v[200:201]
	v_lshl_add_u64 v[136:137], v[136:137], 0, v[202:203]
	global_load_dwordx4 v[148:151], v[136:137], off
	s_nop 0
	global_load_dwordx4 v[136:139], v[136:137], off offset:256
	s_mov_b32 s2, 0x3fd744fd
	v_mov_b32_e32 v226, 0x5800
	v_cmp_gt_u32_e32 vcc, 16, v32
	s_waitcnt vmcnt(0)
	v_cvt_f32_f16_e32 v234, v192
	v_cvt_f32_f16_sdwa v235, v192 dst_sel:DWORD dst_unused:UNUSED_PAD src0_sel:WORD_1
	v_cvt_f32_f16_e32 v192, v193
	v_cvt_f32_f16_sdwa v193, v193 dst_sel:DWORD dst_unused:UNUSED_PAD src0_sel:WORD_1
	v_cvt_f32_f16_e32 v236, v194
	v_cvt_f32_f16_sdwa v237, v194 dst_sel:DWORD dst_unused:UNUSED_PAD src0_sel:WORD_1
	v_cvt_f32_f16_e32 v194, v195
	v_cvt_f32_f16_sdwa v195, v195 dst_sel:DWORD dst_unused:UNUSED_PAD src0_sel:WORD_1
	v_pk_fma_f32 v[130:131], v[192:193], s[2:3], v[130:131] op_sel_hi:[1,0,1]
	v_cvt_f32_f16_e32 v192, v188
	v_cvt_f32_f16_sdwa v193, v188 dst_sel:DWORD dst_unused:UNUSED_PAD src0_sel:WORD_1
	v_pk_fma_f32 v[126:127], v[194:195], s[2:3], v[126:127] op_sel_hi:[1,0,1]
	v_cvt_f32_f16_e32 v188, v189
	v_cvt_f32_f16_sdwa v189, v189 dst_sel:DWORD dst_unused:UNUSED_PAD src0_sel:WORD_1
	v_cvt_f32_f16_e32 v194, v190
	v_cvt_f32_f16_sdwa v195, v190 dst_sel:DWORD dst_unused:UNUSED_PAD src0_sel:WORD_1
	v_cvt_f32_f16_e32 v190, v191
	v_cvt_f32_f16_sdwa v191, v191 dst_sel:DWORD dst_unused:UNUSED_PAD src0_sel:WORD_1
	v_pk_fma_f32 v[122:123], v[188:189], s[2:3], v[122:123] op_sel_hi:[1,0,1]
	v_cvt_f32_f16_e32 v188, v184
	v_cvt_f32_f16_sdwa v189, v184 dst_sel:DWORD dst_unused:UNUSED_PAD src0_sel:WORD_1
	v_pk_fma_f32 v[118:119], v[190:191], s[2:3], v[118:119] op_sel_hi:[1,0,1]
	v_cvt_f32_f16_e32 v184, v185
	v_cvt_f32_f16_sdwa v185, v185 dst_sel:DWORD dst_unused:UNUSED_PAD src0_sel:WORD_1
	v_cvt_f32_f16_e32 v190, v186
	v_cvt_f32_f16_sdwa v191, v186 dst_sel:DWORD dst_unused:UNUSED_PAD src0_sel:WORD_1
	v_cvt_f32_f16_e32 v186, v187
	v_cvt_f32_f16_sdwa v187, v187 dst_sel:DWORD dst_unused:UNUSED_PAD src0_sel:WORD_1
	v_pk_fma_f32 v[114:115], v[184:185], s[2:3], v[114:115] op_sel_hi:[1,0,1]
	v_cvt_f32_f16_e32 v184, v180
	v_cvt_f32_f16_sdwa v185, v180 dst_sel:DWORD dst_unused:UNUSED_PAD src0_sel:WORD_1
	v_pk_fma_f32 v[110:111], v[186:187], s[2:3], v[110:111] op_sel_hi:[1,0,1]
	v_cvt_f32_f16_e32 v180, v181
	v_cvt_f32_f16_sdwa v181, v181 dst_sel:DWORD dst_unused:UNUSED_PAD src0_sel:WORD_1
	v_cvt_f32_f16_e32 v186, v182
	v_cvt_f32_f16_sdwa v187, v182 dst_sel:DWORD dst_unused:UNUSED_PAD src0_sel:WORD_1
	v_cvt_f32_f16_e32 v182, v183
	v_cvt_f32_f16_sdwa v183, v183 dst_sel:DWORD dst_unused:UNUSED_PAD src0_sel:WORD_1
	v_pk_fma_f32 v[106:107], v[180:181], s[2:3], v[106:107] op_sel_hi:[1,0,1]
	v_cvt_f32_f16_e32 v180, v176
	v_cvt_f32_f16_sdwa v181, v176 dst_sel:DWORD dst_unused:UNUSED_PAD src0_sel:WORD_1
	v_pk_fma_f32 v[102:103], v[182:183], s[2:3], v[102:103] op_sel_hi:[1,0,1]
	v_cvt_f32_f16_e32 v176, v177
	v_cvt_f32_f16_sdwa v177, v177 dst_sel:DWORD dst_unused:UNUSED_PAD src0_sel:WORD_1
	v_cvt_f32_f16_e32 v182, v178
	v_cvt_f32_f16_sdwa v183, v178 dst_sel:DWORD dst_unused:UNUSED_PAD src0_sel:WORD_1
	v_cvt_f32_f16_e32 v178, v179
	v_cvt_f32_f16_sdwa v179, v179 dst_sel:DWORD dst_unused:UNUSED_PAD src0_sel:WORD_1
	v_pk_fma_f32 v[98:99], v[176:177], s[2:3], v[98:99] op_sel_hi:[1,0,1]
;     __device__ __forceinline__ void fused(f32x4 (&acc)[2][2][4][2], const GUnit& u, int wr, int wc, int fr, int fq, LAS unsigned char* lds, int wid, int lane) const {
;     ...
;         for (int ai = 0; ai < 2; ++ai)
; #pragma unroll
;             for (int m = 0; m < 4; ++m) {
; #pragma unroll
;                 for (int bj = 0; bj < 2; ++bj) { f32x4 h0, h1; unpk8(hw[ai][m][bj], h0, h1);
;                     acc[ai][bj][m][0] += ALPHA * h0; acc[ai][bj][m][1] += ALPHA * h1;
;                 }
;                 asm volatile("" : "+v"(acc[ai][0][m][0]), "+v"(acc[ai][0][m][1]), "+v"(acc[ai][1][m][0]), "+v"(acc[ai][1][m][1])); } }
	v_cvt_f32_f16_e32 v176, v172
	v_cvt_f32_f16_sdwa v177, v172 dst_sel:DWORD dst_unused:UNUSED_PAD src0_sel:WORD_1
	v_pk_fma_f32 v[94:95], v[178:179], s[2:3], v[94:95] op_sel_hi:[1,0,1]
	v_cvt_f32_f16_e32 v172, v173
	v_cvt_f32_f16_sdwa v173, v173 dst_sel:DWORD dst_unused:UNUSED_PAD src0_sel:WORD_1
	v_cvt_f32_f16_e32 v178, v174
	v_cvt_f32_f16_sdwa v179, v174 dst_sel:DWORD dst_unused:UNUSED_PAD src0_sel:WORD_1
	v_cvt_f32_f16_e32 v174, v175
	v_cvt_f32_f16_sdwa v175, v175 dst_sel:DWORD dst_unused:UNUSED_PAD src0_sel:WORD_1
	v_pk_fma_f32 v[90:91], v[172:173], s[2:3], v[90:91] op_sel_hi:[1,0,1]
	v_cvt_f32_f16_e32 v172, v168
	v_cvt_f32_f16_sdwa v173, v168 dst_sel:DWORD dst_unused:UNUSED_PAD src0_sel:WORD_1
	v_pk_fma_f32 v[86:87], v[174:175], s[2:3], v[86:87] op_sel_hi:[1,0,1]
	v_cvt_f32_f16_e32 v168, v169
	v_cvt_f32_f16_sdwa v169, v169 dst_sel:DWORD dst_unused:UNUSED_PAD src0_sel:WORD_1
	v_cvt_f32_f16_e32 v174, v170
	v_cvt_f32_f16_sdwa v175, v170 dst_sel:DWORD dst_unused:UNUSED_PAD src0_sel:WORD_1
	v_cvt_f32_f16_e32 v170, v171
	v_cvt_f32_f16_sdwa v171, v171 dst_sel:DWORD dst_unused:UNUSED_PAD src0_sel:WORD_1
	v_pk_fma_f32 v[82:83], v[168:169], s[2:3], v[82:83] op_sel_hi:[1,0,1]
	v_cvt_f32_f16_e32 v168, v164
	v_cvt_f32_f16_sdwa v169, v164 dst_sel:DWORD dst_unused:UNUSED_PAD src0_sel:WORD_1
	v_pk_fma_f32 v[78:79], v[170:171], s[2:3], v[78:79] op_sel_hi:[1,0,1]
	v_cvt_f32_f16_e32 v164, v165
	v_cvt_f32_f16_sdwa v165, v165 dst_sel:DWORD dst_unused:UNUSED_PAD src0_sel:WORD_1
	v_cvt_f32_f16_e32 v170, v166
	v_cvt_f32_f16_sdwa v171, v166 dst_sel:DWORD dst_unused:UNUSED_PAD src0_sel:WORD_1
	v_cvt_f32_f16_e32 v166, v167
	v_cvt_f32_f16_sdwa v167, v167 dst_sel:DWORD dst_unused:UNUSED_PAD src0_sel:WORD_1
	v_pk_fma_f32 v[74:75], v[164:165], s[2:3], v[74:75] op_sel_hi:[1,0,1]
	v_cvt_f32_f16_e32 v164, v160
	v_cvt_f32_f16_sdwa v165, v160 dst_sel:DWORD dst_unused:UNUSED_PAD src0_sel:WORD_1
	v_pk_fma_f32 v[70:71], v[166:167], s[2:3], v[70:71] op_sel_hi:[1,0,1]
	v_cvt_f32_f16_e32 v160, v161
	v_cvt_f32_f16_sdwa v161, v161 dst_sel:DWORD dst_unused:UNUSED_PAD src0_sel:WORD_1
	v_cvt_f32_f16_e32 v166, v162
	v_cvt_f32_f16_sdwa v167, v162 dst_sel:DWORD dst_unused:UNUSED_PAD src0_sel:WORD_1
	v_cvt_f32_f16_e32 v162, v163
	v_cvt_f32_f16_sdwa v163, v163 dst_sel:DWORD dst_unused:UNUSED_PAD src0_sel:WORD_1
	v_pk_fma_f32 v[66:67], v[160:161], s[2:3], v[66:67] op_sel_hi:[1,0,1]
	v_cvt_f32_f16_e32 v160, v156
	v_cvt_f32_f16_sdwa v161, v156 dst_sel:DWORD dst_unused:UNUSED_PAD src0_sel:WORD_1
	v_pk_fma_f32 v[62:63], v[162:163], s[2:3], v[62:63] op_sel_hi:[1,0,1]
	v_cvt_f32_f16_e32 v156, v157
	v_cvt_f32_f16_sdwa v157, v157 dst_sel:DWORD dst_unused:UNUSED_PAD src0_sel:WORD_1
	v_cvt_f32_f16_e32 v162, v158
	v_cvt_f32_f16_sdwa v163, v158 dst_sel:DWORD dst_unused:UNUSED_PAD src0_sel:WORD_1
	v_cvt_f32_f16_e32 v158, v159
	v_cvt_f32_f16_sdwa v159, v159 dst_sel:DWORD dst_unused:UNUSED_PAD src0_sel:WORD_1
	v_pk_fma_f32 v[58:59], v[156:157], s[2:3], v[58:59] op_sel_hi:[1,0,1]
	v_cvt_f32_f16_e32 v156, v152
	v_cvt_f32_f16_sdwa v157, v152 dst_sel:DWORD dst_unused:UNUSED_PAD src0_sel:WORD_1
	v_pk_fma_f32 v[54:55], v[158:159], s[2:3], v[54:55] op_sel_hi:[1,0,1]
	v_cvt_f32_f16_e32 v152, v153
	v_cvt_f32_f16_sdwa v153, v153 dst_sel:DWORD dst_unused:UNUSED_PAD src0_sel:WORD_1
	v_cvt_f32_f16_e32 v158, v154
	v_cvt_f32_f16_sdwa v159, v154 dst_sel:DWORD dst_unused:UNUSED_PAD src0_sel:WORD_1
	v_cvt_f32_f16_e32 v154, v155
	v_cvt_f32_f16_sdwa v155, v155 dst_sel:DWORD dst_unused:UNUSED_PAD src0_sel:WORD_1
	v_pk_fma_f32 v[50:51], v[152:153], s[2:3], v[50:51] op_sel_hi:[1,0,1]
	v_cvt_f32_f16_e32 v152, v144
	v_cvt_f32_f16_sdwa v153, v144 dst_sel:DWORD dst_unused:UNUSED_PAD src0_sel:WORD_1
	v_pk_fma_f32 v[46:47], v[154:155], s[2:3], v[46:47] op_sel_hi:[1,0,1]
	v_cvt_f32_f16_e32 v144, v145
	v_cvt_f32_f16_sdwa v145, v145 dst_sel:DWORD dst_unused:UNUSED_PAD src0_sel:WORD_1
	v_cvt_f32_f16_e32 v154, v146
	v_cvt_f32_f16_sdwa v155, v146 dst_sel:DWORD dst_unused:UNUSED_PAD src0_sel:WORD_1
	v_cvt_f32_f16_e32 v146, v147
	v_cvt_f32_f16_sdwa v147, v147 dst_sel:DWORD dst_unused:UNUSED_PAD src0_sel:WORD_1
	v_pk_fma_f32 v[42:43], v[144:145], s[2:3], v[42:43] op_sel_hi:[1,0,1]
	v_cvt_f32_f16_e32 v144, v140
	v_cvt_f32_f16_sdwa v145, v140 dst_sel:DWORD dst_unused:UNUSED_PAD src0_sel:WORD_1
	v_pk_fma_f32 v[38:39], v[146:147], s[2:3], v[38:39] op_sel_hi:[1,0,1]
	v_cvt_f32_f16_e32 v140, v141
	v_cvt_f32_f16_sdwa v141, v141 dst_sel:DWORD dst_unused:UNUSED_PAD src0_sel:WORD_1
	v_cvt_f32_f16_e32 v146, v142
	v_cvt_f32_f16_sdwa v147, v142 dst_sel:DWORD dst_unused:UNUSED_PAD src0_sel:WORD_1
	v_cvt_f32_f16_e32 v142, v143
	v_cvt_f32_f16_sdwa v143, v143 dst_sel:DWORD dst_unused:UNUSED_PAD src0_sel:WORD_1
	v_pk_fma_f32 v[30:31], v[140:141], s[2:3], v[30:31] op_sel_hi:[1,0,1]
	v_cvt_f32_f16_e32 v140, v132
	v_cvt_f32_f16_sdwa v141, v132 dst_sel:DWORD dst_unused:UNUSED_PAD src0_sel:WORD_1
	v_pk_fma_f32 v[26:27], v[142:143], s[2:3], v[26:27] op_sel_hi:[1,0,1]
	v_cvt_f32_f16_e32 v132, v133
	v_cvt_f32_f16_sdwa v133, v133 dst_sel:DWORD dst_unused:UNUSED_PAD src0_sel:WORD_1
	v_cvt_f32_f16_e32 v142, v134
	v_cvt_f32_f16_sdwa v143, v134 dst_sel:DWORD dst_unused:UNUSED_PAD src0_sel:WORD_1
	v_cvt_f32_f16_e32 v134, v135
	v_cvt_f32_f16_sdwa v135, v135 dst_sel:DWORD dst_unused:UNUSED_PAD src0_sel:WORD_1
	v_pk_fma_f32 v[22:23], v[132:133], s[2:3], v[22:23] op_sel_hi:[1,0,1]
	v_cvt_f32_f16_e32 v132, v148
	v_cvt_f32_f16_sdwa v133, v148 dst_sel:DWORD dst_unused:UNUSED_PAD src0_sel:WORD_1
	v_pk_fma_f32 v[18:19], v[134:135], s[2:3], v[18:19] op_sel_hi:[1,0,1]
	v_cvt_f32_f16_e32 v134, v149
	v_cvt_f32_f16_sdwa v135, v149 dst_sel:DWORD dst_unused:UNUSED_PAD src0_sel:WORD_1
; #define LAS __attribute__((address_space(3)))
; __device__ __forceinline__ float shx(float v, int mask) { return __builtin_bit_cast(float, __builtin_amdgcn_ds_bpermute((lane_now() ^ mask) << 2, __builtin_bit_cast(int, v))); }
;     __device__ __forceinline__ void fused(f32x4 (&acc)[2][2][4][2], const GUnit& u, int wr, int wc, int fr, int fq, LAS unsigned char* lds, int wid, int lane) const {
;     ...
;                 for (int bj = 0; bj < 2; ++bj) { f32x4 h0, h1; unpk8(hw[ai][m][bj], h0, h1);
;                     acc[ai][bj][m][0] += ALPHA * h0; acc[ai][bj][m][1] += ALPHA * h1;
;                 }
;                 asm volatile("" : "+v"(acc[ai][0][m][0]), "+v"(acc[ai][0][m][1]), "+v"(acc[ai][1][m][0]), "+v"(acc[ai][1][m][1])); } }
;         LAS f32x2* P = (LAS f32x2*)lds; LAS f32x2* S = (LAS f32x2*)(lds + 8192); LAS unsigned* flag = (LAS unsigned*)(lds + 8192 + 2048);
;         unsigned* xbuf = (unsigned*)(ws + WS_X); unsigned* tmo = (unsigned*)(ws + WS_CTL) + CW_TMO;
; #pragma unroll
;         for (int ai = 0; ai < 2; ++ai)
; #pragma unroll
;             for (int m = 0; m < 4; ++m) {
;                 float s = 0.f;
; #pragma unroll
;                 for (int bj = 0; bj < 2; ++bj)
; #pragma unroll
;                     for (int n = 0; n < 2; ++n) { const f32x4 x = acc[ai][bj][m][n]; s += (x[0] + x[1]) + (x[2] + x[3]); }
;                 s += shx(s, 16); s += shx(s, 32);
	v_pk_fma_f32 v[12:13], v[132:133], s[2:3], v[12:13] op_sel_hi:[1,0,1]
	v_cvt_f32_f16_e32 v132, v136
	v_cvt_f32_f16_sdwa v133, v136 dst_sel:DWORD dst_unused:UNUSED_PAD src0_sel:WORD_1
	v_pk_fma_f32 v[14:15], v[134:135], s[2:3], v[14:15] op_sel_hi:[1,0,1]
	v_cvt_f32_f16_e32 v134, v137
	v_cvt_f32_f16_sdwa v135, v137 dst_sel:DWORD dst_unused:UNUSED_PAD src0_sel:WORD_1
	v_cvt_f32_f16_e32 v136, v138
	v_cvt_f32_f16_sdwa v137, v138 dst_sel:DWORD dst_unused:UNUSED_PAD src0_sel:WORD_1
	v_pk_fma_f32 v[128:129], v[234:235], s[2:3], v[128:129] op_sel_hi:[1,0,1]
	v_pk_fma_f32 v[124:125], v[236:237], s[2:3], v[124:125] op_sel_hi:[1,0,1]
	v_pk_fma_f32 v[120:121], v[192:193], s[2:3], v[120:121] op_sel_hi:[1,0,1]
	v_pk_fma_f32 v[116:117], v[194:195], s[2:3], v[116:117] op_sel_hi:[1,0,1]
	v_cvt_f32_f16_e32 v138, v139
	v_cvt_f32_f16_sdwa v139, v139 dst_sel:DWORD dst_unused:UNUSED_PAD src0_sel:WORD_1
	v_pk_fma_f32 v[6:7], v[134:135], s[2:3], v[6:7] op_sel_hi:[1,0,1]
	v_pk_fma_f32 v[4:5], v[132:133], s[2:3], v[4:5] op_sel_hi:[1,0,1]
	v_pk_fma_f32 v[0:1], v[136:137], s[2:3], v[0:1] op_sel_hi:[1,0,1]
	v_pk_fma_f32 v[20:21], v[140:141], s[2:3], v[20:21] op_sel_hi:[1,0,1]
	v_pk_fma_f32 v[16:17], v[142:143], s[2:3], v[16:17] op_sel_hi:[1,0,1]
	v_cvt_f32_f16_e32 v140, v150
	v_cvt_f32_f16_sdwa v141, v150 dst_sel:DWORD dst_unused:UNUSED_PAD src0_sel:WORD_1
	v_cvt_f32_f16_e32 v142, v151
	v_cvt_f32_f16_sdwa v143, v151 dst_sel:DWORD dst_unused:UNUSED_PAD src0_sel:WORD_1
	v_pk_fma_f32 v[2:3], v[138:139], s[2:3], v[2:3] op_sel_hi:[1,0,1]
	v_pk_fma_f32 v[112:113], v[188:189], s[2:3], v[112:113] op_sel_hi:[1,0,1]
	v_pk_fma_f32 v[108:109], v[190:191], s[2:3], v[108:109] op_sel_hi:[1,0,1]
	v_pk_fma_f32 v[104:105], v[184:185], s[2:3], v[104:105] op_sel_hi:[1,0,1]
	v_pk_fma_f32 v[100:101], v[186:187], s[2:3], v[100:101] op_sel_hi:[1,0,1]
	v_pk_fma_f32 v[96:97], v[180:181], s[2:3], v[96:97] op_sel_hi:[1,0,1]
	v_pk_fma_f32 v[92:93], v[182:183], s[2:3], v[92:93] op_sel_hi:[1,0,1]
	v_pk_fma_f32 v[88:89], v[176:177], s[2:3], v[88:89] op_sel_hi:[1,0,1]
	v_pk_fma_f32 v[84:85], v[178:179], s[2:3], v[84:85] op_sel_hi:[1,0,1]
	v_pk_fma_f32 v[80:81], v[172:173], s[2:3], v[80:81] op_sel_hi:[1,0,1]
	v_pk_fma_f32 v[76:77], v[174:175], s[2:3], v[76:77] op_sel_hi:[1,0,1]
	v_pk_fma_f32 v[72:73], v[168:169], s[2:3], v[72:73] op_sel_hi:[1,0,1]
	v_pk_fma_f32 v[68:69], v[170:171], s[2:3], v[68:69] op_sel_hi:[1,0,1]
	v_pk_fma_f32 v[64:65], v[164:165], s[2:3], v[64:65] op_sel_hi:[1,0,1]
	v_pk_fma_f32 v[60:61], v[166:167], s[2:3], v[60:61] op_sel_hi:[1,0,1]
	v_pk_fma_f32 v[56:57], v[160:161], s[2:3], v[56:57] op_sel_hi:[1,0,1]
	v_pk_fma_f32 v[52:53], v[162:163], s[2:3], v[52:53] op_sel_hi:[1,0,1]
	v_pk_fma_f32 v[48:49], v[156:157], s[2:3], v[48:49] op_sel_hi:[1,0,1]
	v_pk_fma_f32 v[44:45], v[158:159], s[2:3], v[44:45] op_sel_hi:[1,0,1]
	v_pk_fma_f32 v[40:41], v[152:153], s[2:3], v[40:41] op_sel_hi:[1,0,1]
	v_pk_fma_f32 v[36:37], v[154:155], s[2:3], v[36:37] op_sel_hi:[1,0,1]
	v_pk_fma_f32 v[28:29], v[144:145], s[2:3], v[28:29] op_sel_hi:[1,0,1]
	v_pk_fma_f32 v[24:25], v[146:147], s[2:3], v[24:25] op_sel_hi:[1,0,1]
	v_pk_fma_f32 v[10:11], v[142:143], s[2:3], v[10:11] op_sel_hi:[1,0,1]
	v_pk_fma_f32 v[8:9], v[140:141], s[2:3], v[8:9] op_sel_hi:[1,0,1]
	v_readlane_b32 s2, v252, 13
	v_cmp_gt_u32_e32 vcc, 16, v32
	v_pk_add_f32 v[136:137], v[128:129], v[130:131]
	v_pk_add_f32 v[150:151], v[112:113], v[114:115]
	v_pk_add_f32 v[164:165], v[96:97], v[98:99]
	v_pk_add_f32 v[178:179], v[80:81], v[82:83]
	v_pk_add_f32 v[138:139], v[124:125], v[126:127]
	v_pk_add_f32 v[152:153], v[108:109], v[110:111]
	v_pk_add_f32 v[166:167], v[92:93], v[94:95]
	v_pk_add_f32 v[180:181], v[76:77], v[78:79]
	v_pk_add_f32 v[140:141], v[120:121], v[122:123]
	v_pk_add_f32 v[154:155], v[104:105], v[106:107]
	v_pk_add_f32 v[168:169], v[88:89], v[90:91]
	v_pk_add_f32 v[182:183], v[72:73], v[74:75]
	v_pk_add_f32 v[142:143], v[116:117], v[118:119]
	v_pk_add_f32 v[156:157], v[100:101], v[102:103]
	v_pk_add_f32 v[170:171], v[84:85], v[86:87]
	v_pk_add_f32 v[184:185], v[68:69], v[70:71]
	v_pk_add_f32 v[136:137], v[136:137], v[138:139]
	v_pk_add_f32 v[150:151], v[150:151], v[152:153]
	v_pk_add_f32 v[164:165], v[164:165], v[166:167]
	v_pk_add_f32 v[178:179], v[178:179], v[180:181]
	v_pk_add_f32 v[140:141], v[140:141], v[142:143]
	v_pk_add_f32 v[154:155], v[154:155], v[156:157]
	v_pk_add_f32 v[168:169], v[168:169], v[170:171]
	v_pk_add_f32 v[182:183], v[182:183], v[184:185]
	v_pk_add_f32 v[136:137], v[136:137], v[140:141]
	v_pk_add_f32 v[150:151], v[150:151], v[154:155]
	v_pk_add_f32 v[164:165], v[164:165], v[168:169]
	v_pk_add_f32 v[178:179], v[178:179], v[182:183]
	v_add_f32_e32 v145, v136, v137
	v_add_f32_e32 v159, v150, v151
	v_add_f32_e32 v173, v164, v165
	v_add_f32_e32 v187, v178, v179
	v_mov_b32_e32 v148, v145
	v_mov_b32_e32 v162, v159
	v_mov_b32_e32 v176, v173
	v_mov_b32_e32 v190, v187
	v_permlane16_swap_b32 v148, v145
	v_permlane16_swap_b32 v162, v159
	v_permlane16_swap_b32 v176, v173
	v_permlane16_swap_b32 v190, v187
	v_add_f32_e32 v145, v145, v148
	v_add_f32_e32 v159, v159, v162
	v_add_f32_e32 v173, v173, v176
	v_add_f32_e32 v187, v187, v190
	v_mov_b32_e32 v148, v145
	v_mov_b32_e32 v162, v159
	v_mov_b32_e32 v176, v173
	v_mov_b32_e32 v190, v187
	v_permlane32_swap_b32 v148, v145
	v_permlane32_swap_b32 v162, v159
	v_permlane32_swap_b32 v176, v173
	v_permlane32_swap_b32 v190, v187
	v_add_f32_e32 v145, v145, v148
	v_add_f32_e32 v159, v159, v162
	v_add_f32_e32 v173, v173, v176
	v_add_f32_e32 v187, v187, v190
	v_mul_f32_e32 v144, 0x3c800000, v145
	v_mul_f32_e32 v158, 0x3c800000, v159
	v_mul_f32_e32 v172, 0x3c800000, v173
; __device__ __forceinline__ float shx(float v, int mask) { return __builtin_bit_cast(float, __builtin_amdgcn_ds_bpermute((lane_now() ^ mask) << 2, __builtin_bit_cast(int, v))); }
;     __device__ __forceinline__ void fused(f32x4 (&acc)[2][2][4][2], const GUnit& u, int wr, int wc, int fr, int fq, LAS unsigned char* lds, int wid, int lane) const {
;     ...
;                 const float mw = s * (1.0f / 64.0f); float q = 0.f;
; #pragma unroll
;                 for (int bj = 0; bj < 2; ++bj)
; #pragma unroll
;                     for (int n = 0; n < 2; ++n) { const f32x4 d = acc[ai][bj][m][n] - mw; q += (d[0] * d[0] + d[1] * d[1]) + (d[2] * d[2] + d[3] * d[3]); }
;                 q += shx(q, 16); q += shx(q, 32);
	v_mul_f32_e32 v186, 0x3c800000, v187
	v_pk_add_f32 v[136:137], v[128:129], v[144:145] op_sel_hi:[1,0] neg_lo:[0,1] neg_hi:[0,1]
	v_pk_add_f32 v[150:151], v[112:113], v[158:159] op_sel_hi:[1,0] neg_lo:[0,1] neg_hi:[0,1]
	v_pk_add_f32 v[164:165], v[96:97], v[172:173] op_sel_hi:[1,0] neg_lo:[0,1] neg_hi:[0,1]
	v_pk_add_f32 v[178:179], v[80:81], v[186:187] op_sel_hi:[1,0] neg_lo:[0,1] neg_hi:[0,1]
	v_pk_mul_f32 v[146:147], v[136:137], v[136:137]
	v_pk_mul_f32 v[160:161], v[150:151], v[150:151]
	v_pk_mul_f32 v[174:175], v[164:165], v[164:165]
	v_pk_mul_f32 v[188:189], v[178:179], v[178:179]
	v_pk_add_f32 v[138:139], v[130:131], v[144:145] op_sel_hi:[1,0] neg_lo:[0,1] neg_hi:[0,1]
	v_pk_add_f32 v[152:153], v[114:115], v[158:159] op_sel_hi:[1,0] neg_lo:[0,1] neg_hi:[0,1]
	v_pk_add_f32 v[166:167], v[98:99], v[172:173] op_sel_hi:[1,0] neg_lo:[0,1] neg_hi:[0,1]
	v_pk_add_f32 v[180:181], v[82:83], v[186:187] op_sel_hi:[1,0] neg_lo:[0,1] neg_hi:[0,1]
	v_pk_fma_f32 v[146:147], v[138:139], v[138:139], v[146:147]
	v_pk_fma_f32 v[160:161], v[152:153], v[152:153], v[160:161]
	v_pk_fma_f32 v[174:175], v[166:167], v[166:167], v[174:175]
	v_pk_fma_f32 v[188:189], v[180:181], v[180:181], v[188:189]
	v_pk_add_f32 v[140:141], v[124:125], v[144:145] op_sel_hi:[1,0] neg_lo:[0,1] neg_hi:[0,1]
	v_pk_add_f32 v[154:155], v[108:109], v[158:159] op_sel_hi:[1,0] neg_lo:[0,1] neg_hi:[0,1]
	v_pk_add_f32 v[168:169], v[92:93], v[172:173] op_sel_hi:[1,0] neg_lo:[0,1] neg_hi:[0,1]
	v_pk_add_f32 v[182:183], v[76:77], v[186:187] op_sel_hi:[1,0] neg_lo:[0,1] neg_hi:[0,1]
	v_pk_fma_f32 v[146:147], v[140:141], v[140:141], v[146:147]
	v_pk_fma_f32 v[160:161], v[154:155], v[154:155], v[160:161]
	v_pk_fma_f32 v[174:175], v[168:169], v[168:169], v[174:175]
	v_pk_fma_f32 v[188:189], v[182:183], v[182:183], v[188:189]
	v_pk_add_f32 v[142:143], v[126:127], v[144:145] op_sel_hi:[1,0] neg_lo:[0,1] neg_hi:[0,1]
	v_pk_add_f32 v[156:157], v[110:111], v[158:159] op_sel_hi:[1,0] neg_lo:[0,1] neg_hi:[0,1]
	v_pk_add_f32 v[170:171], v[94:95], v[172:173] op_sel_hi:[1,0] neg_lo:[0,1] neg_hi:[0,1]
	v_pk_add_f32 v[184:185], v[78:79], v[186:187] op_sel_hi:[1,0] neg_lo:[0,1] neg_hi:[0,1]
	v_pk_fma_f32 v[146:147], v[142:143], v[142:143], v[146:147]
	v_pk_fma_f32 v[160:161], v[156:157], v[156:157], v[160:161]
	v_pk_fma_f32 v[174:175], v[170:171], v[170:171], v[174:175]
	v_pk_fma_f32 v[188:189], v[184:185], v[184:185], v[188:189]
	v_pk_add_f32 v[136:137], v[120:121], v[144:145] op_sel_hi:[1,0] neg_lo:[0,1] neg_hi:[0,1]
	v_pk_add_f32 v[150:151], v[104:105], v[158:159] op_sel_hi:[1,0] neg_lo:[0,1] neg_hi:[0,1]
	v_pk_add_f32 v[164:165], v[88:89], v[172:173] op_sel_hi:[1,0] neg_lo:[0,1] neg_hi:[0,1]
	v_pk_add_f32 v[178:179], v[72:73], v[186:187] op_sel_hi:[1,0] neg_lo:[0,1] neg_hi:[0,1]
	v_pk_fma_f32 v[146:147], v[136:137], v[136:137], v[146:147]
	v_pk_fma_f32 v[160:161], v[150:151], v[150:151], v[160:161]
	v_pk_fma_f32 v[174:175], v[164:165], v[164:165], v[174:175]
	v_pk_fma_f32 v[188:189], v[178:179], v[178:179], v[188:189]
	v_pk_add_f32 v[138:139], v[122:123], v[144:145] op_sel_hi:[1,0] neg_lo:[0,1] neg_hi:[0,1]
	v_pk_add_f32 v[152:153], v[106:107], v[158:159] op_sel_hi:[1,0] neg_lo:[0,1] neg_hi:[0,1]
	v_pk_add_f32 v[166:167], v[90:91], v[172:173] op_sel_hi:[1,0] neg_lo:[0,1] neg_hi:[0,1]
	v_pk_add_f32 v[180:181], v[74:75], v[186:187] op_sel_hi:[1,0] neg_lo:[0,1] neg_hi:[0,1]
	v_pk_fma_f32 v[146:147], v[138:139], v[138:139], v[146:147]
	v_pk_fma_f32 v[160:161], v[152:153], v[152:153], v[160:161]
	v_pk_fma_f32 v[174:175], v[166:167], v[166:167], v[174:175]
	v_pk_fma_f32 v[188:189], v[180:181], v[180:181], v[188:189]
	v_pk_add_f32 v[140:141], v[116:117], v[144:145] op_sel_hi:[1,0] neg_lo:[0,1] neg_hi:[0,1]
	v_pk_add_f32 v[154:155], v[100:101], v[158:159] op_sel_hi:[1,0] neg_lo:[0,1] neg_hi:[0,1]
	v_pk_add_f32 v[168:169], v[84:85], v[172:173] op_sel_hi:[1,0] neg_lo:[0,1] neg_hi:[0,1]
	v_pk_add_f32 v[182:183], v[68:69], v[186:187] op_sel_hi:[1,0] neg_lo:[0,1] neg_hi:[0,1]
	v_pk_fma_f32 v[146:147], v[140:141], v[140:141], v[146:147]
	v_pk_fma_f32 v[160:161], v[154:155], v[154:155], v[160:161]
	v_pk_fma_f32 v[174:175], v[168:169], v[168:169], v[174:175]
	v_pk_fma_f32 v[188:189], v[182:183], v[182:183], v[188:189]
	v_pk_add_f32 v[142:143], v[118:119], v[144:145] op_sel_hi:[1,0] neg_lo:[0,1] neg_hi:[0,1]
	v_pk_add_f32 v[156:157], v[102:103], v[158:159] op_sel_hi:[1,0] neg_lo:[0,1] neg_hi:[0,1]
	v_pk_add_f32 v[170:171], v[86:87], v[172:173] op_sel_hi:[1,0] neg_lo:[0,1] neg_hi:[0,1]
	v_pk_add_f32 v[184:185], v[70:71], v[186:187] op_sel_hi:[1,0] neg_lo:[0,1] neg_hi:[0,1]
	v_pk_fma_f32 v[146:147], v[142:143], v[142:143], v[146:147]
	v_pk_fma_f32 v[160:161], v[156:157], v[156:157], v[160:161]
	v_pk_fma_f32 v[174:175], v[170:171], v[170:171], v[174:175]
	v_pk_fma_f32 v[188:189], v[184:185], v[184:185], v[188:189]
	v_add_f32_e32 v145, v146, v147
	v_add_f32_e32 v159, v160, v161
	v_add_f32_e32 v173, v174, v175
	v_add_f32_e32 v187, v188, v189
	v_mov_b32_e32 v148, v145
	v_mov_b32_e32 v162, v159
	v_mov_b32_e32 v176, v173
	v_mov_b32_e32 v190, v187
	v_permlane16_swap_b32 v148, v145
	v_permlane16_swap_b32 v162, v159
	v_permlane16_swap_b32 v176, v173
	v_permlane16_swap_b32 v190, v187
	v_add_f32_e32 v145, v145, v148
	v_add_f32_e32 v159, v159, v162
	v_add_f32_e32 v173, v173, v176
	v_add_f32_e32 v187, v187, v190
	v_mov_b32_e32 v148, v145
	v_mov_b32_e32 v162, v159
	v_mov_b32_e32 v176, v173
	v_mov_b32_e32 v190, v187
	v_permlane32_swap_b32 v148, v145
	v_permlane32_swap_b32 v162, v159
	v_permlane32_swap_b32 v176, v173
	v_permlane32_swap_b32 v190, v187
	v_add_f32_e32 v145, v145, v148
	v_add_f32_e32 v159, v159, v162
	v_add_f32_e32 v173, v173, v176
; __device__ __forceinline__ float shx(float v, int mask) { return __builtin_bit_cast(float, __builtin_amdgcn_ds_bpermute((lane_now() ^ mask) << 2, __builtin_bit_cast(int, v))); }
;     __device__ __forceinline__ void fused(f32x4 (&acc)[2][2][4][2], const GUnit& u, int wr, int wc, int fr, int fq, LAS unsigned char* lds, int wid, int lane) const {
;     ...
; #pragma unroll
;         for (int ai = 0; ai < 2; ++ai)
; #pragma unroll
;             for (int m = 0; m < 4; ++m) {
;                 float s = 0.f;
; #pragma unroll
;                 for (int bj = 0; bj < 2; ++bj)
; #pragma unroll
;                     for (int n = 0; n < 2; ++n) { const f32x4 x = acc[ai][bj][m][n]; s += (x[0] + x[1]) + (x[2] + x[3]); }
;                 s += shx(s, 16); s += shx(s, 32);
;                 const float mw = s * (1.0f / 64.0f); float q = 0.f;
; #pragma unroll
;                 for (int bj = 0; bj < 2; ++bj)
; #pragma unroll
;                     for (int n = 0; n < 2; ++n) { const f32x4 d = acc[ai][bj][m][n] - mw; q += (d[0] * d[0] + d[1] * d[1]) + (d[2] * d[2] + d[3] * d[3]); }
;                 q += shx(q, 16); q += shx(q, 32);
;                 if (fq == 0) P[(ai * 128 + wr * 64 + m * 16 + fr) * 4 + wc] = (f32x2){mw, q};
	v_add_f32_e32 v187, v187, v190
	v_lshl_add_u32 v132, v233, 5, s2
	s_and_saveexec_b64 s[4:5], vcc
	ds_write_b64 v132, v[144:145]
	ds_write_b64 v132, v[158:159] offset:512
	ds_write_b64 v132, v[172:173] offset:1024
	ds_write_b64 v132, v[186:187] offset:1536
	s_or_b64 exec, exec, s[4:5]
	v_pk_add_f32 v[136:137], v[64:65], v[66:67]
	v_pk_add_f32 v[150:151], v[48:49], v[50:51]
	v_pk_add_f32 v[164:165], v[28:29], v[30:31]
	v_pk_add_f32 v[178:179], v[12:13], v[14:15]
	v_pk_add_f32 v[138:139], v[60:61], v[62:63]
	v_pk_add_f32 v[152:153], v[44:45], v[46:47]
	v_pk_add_f32 v[166:167], v[24:25], v[26:27]
	v_pk_add_f32 v[180:181], v[8:9], v[10:11]
	v_pk_add_f32 v[140:141], v[56:57], v[58:59]
	v_pk_add_f32 v[154:155], v[40:41], v[42:43]
	v_pk_add_f32 v[168:169], v[20:21], v[22:23]
	v_pk_add_f32 v[182:183], v[4:5], v[6:7]
	v_pk_add_f32 v[142:143], v[52:53], v[54:55]
	v_pk_add_f32 v[156:157], v[36:37], v[38:39]
	v_pk_add_f32 v[170:171], v[16:17], v[18:19]
	v_pk_add_f32 v[184:185], v[0:1], v[2:3]
	v_pk_add_f32 v[136:137], v[136:137], v[138:139]
	v_pk_add_f32 v[150:151], v[150:151], v[152:153]
	v_pk_add_f32 v[164:165], v[164:165], v[166:167]
	v_pk_add_f32 v[178:179], v[178:179], v[180:181]
	v_pk_add_f32 v[140:141], v[140:141], v[142:143]
	v_pk_add_f32 v[154:155], v[154:155], v[156:157]
	v_pk_add_f32 v[168:169], v[168:169], v[170:171]
	v_pk_add_f32 v[182:183], v[182:183], v[184:185]
	v_pk_add_f32 v[136:137], v[136:137], v[140:141]
	v_pk_add_f32 v[150:151], v[150:151], v[154:155]
	v_pk_add_f32 v[164:165], v[164:165], v[168:169]
	v_pk_add_f32 v[178:179], v[178:179], v[182:183]
	v_add_f32_e32 v145, v136, v137
	v_add_f32_e32 v159, v150, v151
	v_add_f32_e32 v173, v164, v165
	v_add_f32_e32 v187, v178, v179
	v_mov_b32_e32 v148, v145
	v_mov_b32_e32 v162, v159
	v_mov_b32_e32 v176, v173
	v_mov_b32_e32 v190, v187
	v_permlane16_swap_b32 v148, v145
	v_permlane16_swap_b32 v162, v159
	v_permlane16_swap_b32 v176, v173
	v_permlane16_swap_b32 v190, v187
	v_add_f32_e32 v145, v145, v148
	v_add_f32_e32 v159, v159, v162
	v_add_f32_e32 v173, v173, v176
	v_add_f32_e32 v187, v187, v190
	v_mov_b32_e32 v148, v145
	v_mov_b32_e32 v162, v159
	v_mov_b32_e32 v176, v173
	v_mov_b32_e32 v190, v187
	v_permlane32_swap_b32 v148, v145
	v_permlane32_swap_b32 v162, v159
	v_permlane32_swap_b32 v176, v173
	v_permlane32_swap_b32 v190, v187
	v_add_f32_e32 v145, v145, v148
	v_add_f32_e32 v159, v159, v162
	v_add_f32_e32 v173, v173, v176
	v_add_f32_e32 v187, v187, v190
	v_mul_f32_e32 v144, 0x3c800000, v145
	v_mul_f32_e32 v158, 0x3c800000, v159
	v_mul_f32_e32 v172, 0x3c800000, v173
	v_mul_f32_e32 v186, 0x3c800000, v187
	v_pk_add_f32 v[136:137], v[64:65], v[144:145] op_sel_hi:[1,0] neg_lo:[0,1] neg_hi:[0,1]
	v_pk_add_f32 v[150:151], v[48:49], v[158:159] op_sel_hi:[1,0] neg_lo:[0,1] neg_hi:[0,1]
	v_pk_add_f32 v[164:165], v[28:29], v[172:173] op_sel_hi:[1,0] neg_lo:[0,1] neg_hi:[0,1]
	v_pk_add_f32 v[178:179], v[12:13], v[186:187] op_sel_hi:[1,0] neg_lo:[0,1] neg_hi:[0,1]
	v_pk_mul_f32 v[146:147], v[136:137], v[136:137]
	v_pk_mul_f32 v[160:161], v[150:151], v[150:151]
	v_pk_mul_f32 v[174:175], v[164:165], v[164:165]
	v_pk_mul_f32 v[188:189], v[178:179], v[178:179]
	v_pk_add_f32 v[138:139], v[66:67], v[144:145] op_sel_hi:[1,0] neg_lo:[0,1] neg_hi:[0,1]
	v_pk_add_f32 v[152:153], v[50:51], v[158:159] op_sel_hi:[1,0] neg_lo:[0,1] neg_hi:[0,1]
	v_pk_add_f32 v[166:167], v[30:31], v[172:173] op_sel_hi:[1,0] neg_lo:[0,1] neg_hi:[0,1]
	v_pk_add_f32 v[180:181], v[14:15], v[186:187] op_sel_hi:[1,0] neg_lo:[0,1] neg_hi:[0,1]
	v_pk_fma_f32 v[146:147], v[138:139], v[138:139], v[146:147]
	v_pk_fma_f32 v[160:161], v[152:153], v[152:153], v[160:161]
	v_pk_fma_f32 v[174:175], v[166:167], v[166:167], v[174:175]
	v_pk_fma_f32 v[188:189], v[180:181], v[180:181], v[188:189]
	v_pk_add_f32 v[140:141], v[60:61], v[144:145] op_sel_hi:[1,0] neg_lo:[0,1] neg_hi:[0,1]
	v_pk_add_f32 v[154:155], v[44:45], v[158:159] op_sel_hi:[1,0] neg_lo:[0,1] neg_hi:[0,1]
	v_pk_add_f32 v[168:169], v[24:25], v[172:173] op_sel_hi:[1,0] neg_lo:[0,1] neg_hi:[0,1]
	v_pk_add_f32 v[182:183], v[8:9], v[186:187] op_sel_hi:[1,0] neg_lo:[0,1] neg_hi:[0,1]
	v_pk_fma_f32 v[146:147], v[140:141], v[140:141], v[146:147]
	v_pk_fma_f32 v[160:161], v[154:155], v[154:155], v[160:161]
	v_pk_fma_f32 v[174:175], v[168:169], v[168:169], v[174:175]
	v_pk_fma_f32 v[188:189], v[182:183], v[182:183], v[188:189]
	v_pk_add_f32 v[142:143], v[62:63], v[144:145] op_sel_hi:[1,0] neg_lo:[0,1] neg_hi:[0,1]
	v_pk_add_f32 v[156:157], v[46:47], v[158:159] op_sel_hi:[1,0] neg_lo:[0,1] neg_hi:[0,1]
	v_pk_add_f32 v[170:171], v[26:27], v[172:173] op_sel_hi:[1,0] neg_lo:[0,1] neg_hi:[0,1]
	v_pk_add_f32 v[184:185], v[10:11], v[186:187] op_sel_hi:[1,0] neg_lo:[0,1] neg_hi:[0,1]
	v_pk_fma_f32 v[146:147], v[142:143], v[142:143], v[146:147]
	v_pk_fma_f32 v[160:161], v[156:157], v[156:157], v[160:161]
	v_pk_fma_f32 v[174:175], v[170:171], v[170:171], v[174:175]
	v_pk_fma_f32 v[188:189], v[184:185], v[184:185], v[188:189]
	v_pk_add_f32 v[136:137], v[56:57], v[144:145] op_sel_hi:[1,0] neg_lo:[0,1] neg_hi:[0,1]
; __device__ __forceinline__ float shx(float v, int mask) { return __builtin_bit_cast(float, __builtin_amdgcn_ds_bpermute((lane_now() ^ mask) << 2, __builtin_bit_cast(int, v))); }
;     __device__ __forceinline__ void fused(f32x4 (&acc)[2][2][4][2], const GUnit& u, int wr, int wc, int fr, int fq, LAS unsigned char* lds, int wid, int lane) const {
;     ...
;                     for (int n = 0; n < 2; ++n) { const f32x4 d = acc[ai][bj][m][n] - mw; q += (d[0] * d[0] + d[1] * d[1]) + (d[2] * d[2] + d[3] * d[3]); }
;                 q += shx(q, 16); q += shx(q, 32);
;                 if (fq == 0) P[(ai * 128 + wr * 64 + m * 16 + fr) * 4 + wc] = (f32x2){mw, q};
;             }
;         asm volatile("s_waitcnt lgkmcnt(0)" ::: "memory"); __builtin_amdgcn_s_barrier(); asm volatile("" ::: "memory");
;         const int prow = wid * 32 + (lane & 31);
;         if (lane < 32) {
;             const f32x2 a = P[prow * 4 + 0], b = P[prow * 4 + 1], c = P[prow * 4 + 2], d = P[prow * 4 + 3];
;             const float mt = (a.x + b.x + c.x + d.x) * 0.25f;
;             const float da = a.x - mt, db = b.x - mt, dc = c.x - mt, dd = d.x - mt;
;             const float m2 = (a.y + b.y) + (c.y + d.y) + 64.0f * ((da * da + db * db) + (dc * dc + dd * dd));
;             unsigned long long* slot = (unsigned long long*)xbuf + ((size_t)(u.pm * 256 + prow) * 4 + u.pn);
;             __hip_atomic_store(slot, ((unsigned long long)__float_as_uint(m2) << 32) | __float_as_uint(mt), __ATOMIC_RELAXED, __HIP_MEMORY_SCOPE_AGENT);
	v_pk_add_f32 v[150:151], v[40:41], v[158:159] op_sel_hi:[1,0] neg_lo:[0,1] neg_hi:[0,1]
	v_pk_add_f32 v[164:165], v[20:21], v[172:173] op_sel_hi:[1,0] neg_lo:[0,1] neg_hi:[0,1]
	v_pk_add_f32 v[178:179], v[4:5], v[186:187] op_sel_hi:[1,0] neg_lo:[0,1] neg_hi:[0,1]
	v_pk_fma_f32 v[146:147], v[136:137], v[136:137], v[146:147]
	v_pk_fma_f32 v[160:161], v[150:151], v[150:151], v[160:161]
	v_pk_fma_f32 v[174:175], v[164:165], v[164:165], v[174:175]
	v_pk_fma_f32 v[188:189], v[178:179], v[178:179], v[188:189]
	v_pk_add_f32 v[138:139], v[58:59], v[144:145] op_sel_hi:[1,0] neg_lo:[0,1] neg_hi:[0,1]
	v_pk_add_f32 v[152:153], v[42:43], v[158:159] op_sel_hi:[1,0] neg_lo:[0,1] neg_hi:[0,1]
	v_pk_add_f32 v[166:167], v[22:23], v[172:173] op_sel_hi:[1,0] neg_lo:[0,1] neg_hi:[0,1]
	v_pk_add_f32 v[180:181], v[6:7], v[186:187] op_sel_hi:[1,0] neg_lo:[0,1] neg_hi:[0,1]
	v_pk_fma_f32 v[146:147], v[138:139], v[138:139], v[146:147]
	v_pk_fma_f32 v[160:161], v[152:153], v[152:153], v[160:161]
	v_pk_fma_f32 v[174:175], v[166:167], v[166:167], v[174:175]
	v_pk_fma_f32 v[188:189], v[180:181], v[180:181], v[188:189]
	v_pk_add_f32 v[140:141], v[52:53], v[144:145] op_sel_hi:[1,0] neg_lo:[0,1] neg_hi:[0,1]
	v_pk_add_f32 v[154:155], v[36:37], v[158:159] op_sel_hi:[1,0] neg_lo:[0,1] neg_hi:[0,1]
	v_pk_add_f32 v[168:169], v[16:17], v[172:173] op_sel_hi:[1,0] neg_lo:[0,1] neg_hi:[0,1]
	v_pk_add_f32 v[182:183], v[0:1], v[186:187] op_sel_hi:[1,0] neg_lo:[0,1] neg_hi:[0,1]
	v_pk_fma_f32 v[146:147], v[140:141], v[140:141], v[146:147]
	v_pk_fma_f32 v[160:161], v[154:155], v[154:155], v[160:161]
	v_pk_fma_f32 v[174:175], v[168:169], v[168:169], v[174:175]
	v_pk_fma_f32 v[188:189], v[182:183], v[182:183], v[188:189]
	v_pk_add_f32 v[142:143], v[54:55], v[144:145] op_sel_hi:[1,0] neg_lo:[0,1] neg_hi:[0,1]
	v_pk_add_f32 v[156:157], v[38:39], v[158:159] op_sel_hi:[1,0] neg_lo:[0,1] neg_hi:[0,1]
	v_pk_add_f32 v[170:171], v[18:19], v[172:173] op_sel_hi:[1,0] neg_lo:[0,1] neg_hi:[0,1]
	v_pk_add_f32 v[184:185], v[2:3], v[186:187] op_sel_hi:[1,0] neg_lo:[0,1] neg_hi:[0,1]
	v_pk_fma_f32 v[146:147], v[142:143], v[142:143], v[146:147]
	v_pk_fma_f32 v[160:161], v[156:157], v[156:157], v[160:161]
	v_pk_fma_f32 v[174:175], v[170:171], v[170:171], v[174:175]
	v_pk_fma_f32 v[188:189], v[184:185], v[184:185], v[188:189]
	v_add_f32_e32 v145, v146, v147
	v_add_f32_e32 v159, v160, v161
	v_add_f32_e32 v173, v174, v175
	v_add_f32_e32 v187, v188, v189
	v_mov_b32_e32 v148, v145
	v_mov_b32_e32 v162, v159
	v_mov_b32_e32 v176, v173
	v_mov_b32_e32 v190, v187
	v_permlane16_swap_b32 v148, v145
	v_permlane16_swap_b32 v162, v159
	v_permlane16_swap_b32 v176, v173
	v_permlane16_swap_b32 v190, v187
	v_add_f32_e32 v145, v145, v148
	v_add_f32_e32 v159, v159, v162
	v_add_f32_e32 v173, v173, v176
	v_add_f32_e32 v187, v187, v190
	v_mov_b32_e32 v148, v145
	v_mov_b32_e32 v162, v159
	v_mov_b32_e32 v176, v173
	v_mov_b32_e32 v190, v187
	v_permlane32_swap_b32 v148, v145
	v_permlane32_swap_b32 v162, v159
	v_permlane32_swap_b32 v176, v173
	v_permlane32_swap_b32 v190, v187
	v_add_f32_e32 v145, v145, v148
	v_add_f32_e32 v159, v159, v162
	v_add_f32_e32 v173, v173, v176
	v_add_f32_e32 v187, v187, v190
	s_and_saveexec_b64 s[4:5], vcc
	ds_write_b64 v132, v[144:145] offset:4096
	ds_write_b64 v132, v[158:159] offset:4608
	ds_write_b64 v132, v[172:173] offset:5120
	ds_write_b64 v132, v[186:187] offset:5632
	s_or_b64 exec, exec, s[4:5]
	v_readlane_b32 s2, v251, 8
	s_waitcnt lgkmcnt(0)
	s_barrier
	v_cmp_gt_i32_e64 s[4:5], 32, v32
	v_and_or_b32 v134, v32, 31, s2
	v_add_u32_e32 v132, s14, v134
	v_ashrrev_i32_e32 v133, 31, v132
	s_and_saveexec_b64 s[2:3], s[4:5]
	s_cbranch_execz .LBB0_451
	s_waitcnt lgkmcnt(0)
	v_mov_b32_e32 v146, 0x24970
	ds_read_b32 v146, v146
	v_lshl_add_u32 v135, v134, 5, 0
	ds_read_b128 v[136:139], v135
	ds_read_b128 v[140:143], v135 offset:16
	v_readlane_b32 s6, v252, 14
	v_readlane_b32 s7, v252, 15
	s_ashr_i32 s35, s34, 31
	s_waitcnt lgkmcnt(1)
	v_add_f32_e32 v135, v136, v138
	s_waitcnt lgkmcnt(0)
	v_add_f32_e32 v135, v135, v140
	v_add_f32_e32 v135, v135, v142
	v_fmamk_f32 v136, v135, 0xbe800000, v136
	v_fmac_f32_e32 v138, 0xbe800000, v135
	v_fmamk_f32 v140, v135, 0xbe800000, v140
	v_fmac_f32_e32 v142, 0xbe800000, v135
	v_mul_f32_e32 v147, v136, v136
	v_mul_f32_e32 v149, v138, v138
	v_mul_f32_e32 v151, v140, v140
	v_mul_f32_e32 v153, v142, v142
	v_mov_b32_e32 v146, v137
	v_mov_b32_e32 v148, v139
	v_mov_b32_e32 v150, v141
	v_mov_b32_e32 v152, v143
	v_pk_add_f32 v[136:137], v[146:147], v[148:149]
	v_pk_add_f32 v[138:139], v[150:151], v[152:153]
	v_mul_f32_e32 v144, 0x3e800000, v135
	v_pk_add_f32 v[136:137], v[136:137], v[138:139]
	v_lshlrev_b64 v[138:139], 5, v[132:133]
	v_fmac_f32_e32 v136, 0x42800000, v137
	v_lshl_add_u64 v[138:139], s[6:7], 0, v[138:139]
	v_lshl_add_u64 v[138:139], s[34:35], 3, v[138:139]
	v_mov_b32_e32 v145, v136
	v_readfirstlane_b32 s98, v146
	s_nop 3
	s_cmp_eq_u32 s98, 0
	s_cbranch_scc1 .Lslot_sc1
	global_store_dwordx2 v[138:139], v[144:145], off
	s_branch .Lslot_done
